# GU K-loop back-edge rotation: loop control and next-iteration pointer selection moved behind the last DMA of the previous load segment, LDS read bases kept in v222-v225 (on keep_v8)
# baseline (speedup 1.0000x reference)
.LBB0_845:
	s_ashr_i32 s25, s24, 31
	s_lshl_b64 s[26:27], s[24:25], 19
	s_add_u32 s36, s4, s26
	s_addc_u32 s37, s5, s27
	s_and_b64 s[26:27], s[2:3], exec
	s_cselect_b32 s25, s37, s97
	s_cselect_b32 s28, s36, s96
	s_ashr_i32 s23, s22, 31
	s_lshl_b64 s[26:27], s[22:23], 19
	s_add_u32 s26, s41, s26
	s_addc_u32 s27, s42, s27
	s_and_b64 s[78:79], s[2:3], exec
	s_cselect_b32 s23, s27, s39
	s_cselect_b32 s29, s26, s38
	s_add_u32 s96, s96, 0x40080
	s_addc_u32 s97, s97, 0
	s_add_u32 s53, s38, 0x100
	v_mov_b32_e32 v2, 0
	s_addc_u32 s61, s39, 0
	s_mov_b32 s75, -2
	v_mov_b64_e32 v[2:3], 0
	v_mov_b64_e32 v[4:5], 0
	v_mov_b64_e32 v[6:7], 0
	v_mov_b64_e32 v[8:9], 0
	v_mov_b64_e32 v[10:11], 0
	v_mov_b64_e32 v[12:13], 0
	v_mov_b64_e32 v[14:15], 0
	v_mov_b64_e32 v[16:17], 0
	v_mov_b64_e32 v[18:19], 0
	v_mov_b64_e32 v[20:21], 0
	v_mov_b64_e32 v[22:23], 0
	v_mov_b64_e32 v[24:25], 0
	v_mov_b64_e32 v[26:27], 0
	v_mov_b64_e32 v[28:29], 0
	v_mov_b64_e32 v[30:31], 0
	v_mov_b64_e32 v[32:33], 0
	v_mov_b64_e32 v[34:35], 0
	v_mov_b64_e32 v[36:37], 0
	v_mov_b64_e32 v[38:39], 0
	v_mov_b64_e32 v[40:41], 0
	v_mov_b64_e32 v[42:43], 0
	v_mov_b64_e32 v[44:45], 0
	v_mov_b64_e32 v[46:47], 0
	v_mov_b64_e32 v[48:49], 0
	v_mov_b64_e32 v[50:51], 0
	v_mov_b64_e32 v[52:53], 0
	v_mov_b64_e32 v[54:55], 0
	v_mov_b64_e32 v[56:57], 0
	v_mov_b64_e32 v[58:59], 0
	v_mov_b64_e32 v[60:61], 0
	v_mov_b64_e32 v[62:63], 0
	v_mov_b64_e32 v[64:65], 0
	v_mov_b64_e32 v[66:67], 0
	v_mov_b64_e32 v[68:69], 0
	v_mov_b64_e32 v[70:71], 0
	v_mov_b64_e32 v[72:73], 0
	v_mov_b64_e32 v[74:75], 0
	v_mov_b64_e32 v[76:77], 0
	v_mov_b64_e32 v[78:79], 0
	v_mov_b64_e32 v[80:81], 0
	v_mov_b64_e32 v[82:83], 0
	v_mov_b64_e32 v[84:85], 0
	v_mov_b64_e32 v[86:87], 0
	v_mov_b64_e32 v[88:89], 0
	v_mov_b64_e32 v[90:91], 0
	v_mov_b64_e32 v[92:93], 0
	v_mov_b64_e32 v[94:95], 0
	v_mov_b64_e32 v[96:97], 0
	v_mov_b64_e32 v[98:99], 0
	v_mov_b64_e32 v[100:101], 0
	v_mov_b64_e32 v[102:103], 0
	v_mov_b64_e32 v[104:105], 0
	v_mov_b64_e32 v[106:107], 0
	v_mov_b64_e32 v[108:109], 0
	v_mov_b64_e32 v[110:111], 0
	v_mov_b64_e32 v[112:113], 0
	v_mov_b64_e32 v[114:115], 0
	v_mov_b64_e32 v[116:117], 0
	v_mov_b64_e32 v[118:119], 0
	v_mov_b64_e32 v[120:121], 0
	v_mov_b64_e32 v[122:123], 0
	v_mov_b64_e32 v[124:125], 0
	v_mov_b64_e32 v[126:127], 0
	v_mov_b64_e32 v[128:129], 0
	s_add_u32 s9, s96, 0xfffc0080
	s_addc_u32 s38, s97, -1
	s_cmp_eq_u32 s75, 12
	s_cselect_b32 vcc_hi, s25, s38
	s_cselect_b32 vcc_lo, s28, s9
	s_cselect_b32 s39, s23, s61
	s_cselect_b32 s38, s29, s53
	v_add_u32_e32 v222, 0x10000, v145
	v_add_u32_e32 v223, 0x14000, v145
	v_add_u32_e32 v224, 0x18000, v145
	v_add_u32_e32 v225, 0x1c000, v145
	.p2align 6
.LBB0_846:
	ds_read_b128 v[140:143], v222
	ds_read_b128 v[156:159], v222 offset:1024
	ds_read_b128 v[160:163], v222 offset:2048
	ds_read_b128 v[164:167], v222 offset:3072
	ds_read_b128 v[168:171], v223
	ds_read_b128 v[172:175], v223 offset:1024
	ds_read_b128 v[176:179], v223 offset:2048
	ds_read_b128 v[180:183], v223 offset:3072
	v_lshl_add_u64 v[148:149], s[96:97], 0, v[136:137]
	s_add_i32 m0, s46, 0xc000
	ds_read_b128 v[184:187], v147
	ds_read_b128 v[188:191], v147 offset:1024
	ds_read_b128 v[192:195], v147 offset:2048
	ds_read_b128 v[196:199], v147 offset:3072
	ds_read_b128 v[200:203], v147 offset:4096
	ds_read_b128 v[204:207], v147 offset:5120
	ds_read_b128 v[208:211], v147 offset:6144
	ds_read_b128 v[212:215], v147 offset:7168
	global_load_lds_dwordx4 v[148:149], off
	s_add_i32 m0, s46, 0xe000
	v_lshl_add_u64 v[148:149], s[96:97], 0, v[138:139]
	global_load_lds_dwordx4 v[148:149], off
	s_waitcnt vmcnt(8)
	s_waitcnt lgkmcnt(0)
	s_barrier
	s_setprio 1
	v_mfma_f32_16x16x32_bf16 v[126:129], v[140:143], v[184:187], v[126:129]
	v_mfma_f32_16x16x32_bf16 v[118:121], v[160:163], v[184:187], v[118:121]
	v_mfma_f32_16x16x32_bf16 v[110:113], v[140:143], v[192:195], v[110:113]
	v_mfma_f32_16x16x32_bf16 v[102:105], v[160:163], v[192:195], v[102:105]
	v_mfma_f32_16x16x32_bf16 v[94:97], v[140:143], v[200:203], v[94:97]
	v_mfma_f32_16x16x32_bf16 v[86:89], v[160:163], v[200:203], v[86:89]
	v_mfma_f32_16x16x32_bf16 v[78:81], v[140:143], v[208:211], v[78:81]
	v_mfma_f32_16x16x32_bf16 v[70:73], v[160:163], v[208:211], v[70:73]
	v_mfma_f32_16x16x32_bf16 v[126:129], v[156:159], v[188:191], v[126:129]
	v_mfma_f32_16x16x32_bf16 v[118:121], v[164:167], v[188:191], v[118:121]
	v_mfma_f32_16x16x32_bf16 v[110:113], v[156:159], v[196:199], v[110:113]
	v_mfma_f32_16x16x32_bf16 v[102:105], v[164:167], v[196:199], v[102:105]
	v_mfma_f32_16x16x32_bf16 v[94:97], v[156:159], v[204:207], v[94:97]
	v_mfma_f32_16x16x32_bf16 v[86:89], v[164:167], v[204:207], v[86:89]
	v_mfma_f32_16x16x32_bf16 v[78:81], v[156:159], v[212:215], v[78:81]
	v_mfma_f32_16x16x32_bf16 v[70:73], v[164:167], v[212:215], v[70:73]
	v_mfma_f32_16x16x32_bf16 v[122:125], v[168:171], v[184:187], v[122:125]
	v_mfma_f32_16x16x32_bf16 v[114:117], v[176:179], v[184:187], v[114:117]
	v_mfma_f32_16x16x32_bf16 v[106:109], v[168:171], v[192:195], v[106:109]
	v_mfma_f32_16x16x32_bf16 v[98:101], v[176:179], v[192:195], v[98:101]
	v_mfma_f32_16x16x32_bf16 v[90:93], v[168:171], v[200:203], v[90:93]
	v_mfma_f32_16x16x32_bf16 v[82:85], v[176:179], v[200:203], v[82:85]
	v_mfma_f32_16x16x32_bf16 v[74:77], v[168:171], v[208:211], v[74:77]
	v_mfma_f32_16x16x32_bf16 v[66:69], v[176:179], v[208:211], v[66:69]
	v_mfma_f32_16x16x32_bf16 v[122:125], v[172:175], v[188:191], v[122:125]
	v_mfma_f32_16x16x32_bf16 v[114:117], v[180:183], v[188:191], v[114:117]
	v_mfma_f32_16x16x32_bf16 v[106:109], v[172:175], v[196:199], v[106:109]
	v_mfma_f32_16x16x32_bf16 v[98:101], v[180:183], v[196:199], v[98:101]
	v_mfma_f32_16x16x32_bf16 v[90:93], v[172:175], v[204:207], v[90:93]
	v_mfma_f32_16x16x32_bf16 v[82:85], v[180:183], v[204:207], v[82:85]
	v_mfma_f32_16x16x32_bf16 v[74:77], v[172:175], v[212:215], v[74:77]
	v_mfma_f32_16x16x32_bf16 v[66:69], v[180:183], v[212:215], v[66:69]
	s_setprio 0
	s_barrier
	s_add_i32 s78, s45, 0x10000
	v_lshl_add_u64 v[148:149], s[38:39], 0, v[0:1]
	s_mov_b32 m0, s78
	ds_read_b128 v[184:187], v147 offset:16384
	ds_read_b128 v[188:191], v147 offset:17408
	ds_read_b128 v[192:195], v147 offset:18432
	ds_read_b128 v[196:199], v147 offset:19456
	ds_read_b128 v[200:203], v147 offset:20480
	ds_read_b128 v[204:207], v147 offset:21504
	ds_read_b128 v[208:211], v147 offset:22528
	ds_read_b128 v[212:215], v147 offset:23552
	global_load_lds_dwordx4 v[148:149], off
	s_add_i32 m0, s78, 0x2000
	s_add_u32 s78, s38, 0x40000
	v_lshl_add_u64 v[150:151], s[38:39], 0, v[134:135]
	s_addc_u32 s79, s39, 0
	s_add_i32 s9, s45, 0x14000
	global_load_lds_dwordx4 v[150:151], off
	v_lshl_add_u64 v[216:217], s[78:79], 0, v[0:1]
	s_mov_b32 m0, s9
	v_lshl_add_u64 v[218:219], vcc, 0, v[132:133]
	global_load_lds_dwordx4 v[216:217], off
	s_add_i32 m0, s9, 0x2000
	v_lshl_add_u64 v[216:217], s[78:79], 0, v[134:135]
	global_load_lds_dwordx4 v[216:217], off
	s_mov_b32 m0, s46
	v_lshl_add_u64 v[216:217], vcc, 0, v[130:131]
	global_load_lds_dwordx4 v[216:217], off
	s_mov_b32 m0, s47
	s_nop 0
	global_load_lds_dwordx4 v[218:219], off
	s_waitcnt vmcnt(8)
	s_waitcnt lgkmcnt(0)
	s_barrier
	s_setprio 1
	v_mfma_f32_16x16x32_bf16 v[62:65], v[140:143], v[184:187], v[62:65]
	v_mfma_f32_16x16x32_bf16 v[54:57], v[160:163], v[184:187], v[54:57]
	v_mfma_f32_16x16x32_bf16 v[46:49], v[140:143], v[192:195], v[46:49]
	v_mfma_f32_16x16x32_bf16 v[38:41], v[160:163], v[192:195], v[38:41]
	v_mfma_f32_16x16x32_bf16 v[30:33], v[140:143], v[200:203], v[30:33]
	v_mfma_f32_16x16x32_bf16 v[22:25], v[160:163], v[200:203], v[22:25]
	v_mfma_f32_16x16x32_bf16 v[14:17], v[140:143], v[208:211], v[14:17]
	v_mfma_f32_16x16x32_bf16 v[6:9], v[160:163], v[208:211], v[6:9]
	v_mfma_f32_16x16x32_bf16 v[62:65], v[156:159], v[188:191], v[62:65]
	v_mfma_f32_16x16x32_bf16 v[54:57], v[164:167], v[188:191], v[54:57]
	v_mfma_f32_16x16x32_bf16 v[46:49], v[156:159], v[196:199], v[46:49]
	v_mfma_f32_16x16x32_bf16 v[38:41], v[164:167], v[196:199], v[38:41]
	v_mfma_f32_16x16x32_bf16 v[30:33], v[156:159], v[204:207], v[30:33]
	v_mfma_f32_16x16x32_bf16 v[22:25], v[164:167], v[204:207], v[22:25]
	v_mfma_f32_16x16x32_bf16 v[14:17], v[156:159], v[212:215], v[14:17]
	v_mfma_f32_16x16x32_bf16 v[6:9], v[164:167], v[212:215], v[6:9]
	v_mfma_f32_16x16x32_bf16 v[58:61], v[168:171], v[184:187], v[58:61]
	v_mfma_f32_16x16x32_bf16 v[50:53], v[176:179], v[184:187], v[50:53]
	v_mfma_f32_16x16x32_bf16 v[42:45], v[168:171], v[192:195], v[42:45]
	v_mfma_f32_16x16x32_bf16 v[34:37], v[176:179], v[192:195], v[34:37]
	v_mfma_f32_16x16x32_bf16 v[26:29], v[168:171], v[200:203], v[26:29]
	v_mfma_f32_16x16x32_bf16 v[18:21], v[176:179], v[200:203], v[18:21]
	v_mfma_f32_16x16x32_bf16 v[10:13], v[168:171], v[208:211], v[10:13]
	v_mfma_f32_16x16x32_bf16 v[2:5], v[176:179], v[208:211], v[2:5]
	v_mfma_f32_16x16x32_bf16 v[58:61], v[172:175], v[188:191], v[58:61]
	v_mfma_f32_16x16x32_bf16 v[50:53], v[180:183], v[188:191], v[50:53]
	v_mfma_f32_16x16x32_bf16 v[42:45], v[172:175], v[196:199], v[42:45]
	v_mfma_f32_16x16x32_bf16 v[34:37], v[180:183], v[196:199], v[34:37]
	v_mfma_f32_16x16x32_bf16 v[26:29], v[172:175], v[204:207], v[26:29]
	v_mfma_f32_16x16x32_bf16 v[18:21], v[180:183], v[204:207], v[18:21]
	v_mfma_f32_16x16x32_bf16 v[10:13], v[172:175], v[212:215], v[10:13]
	v_mfma_f32_16x16x32_bf16 v[2:5], v[180:183], v[212:215], v[2:5]
	s_setprio 0
	s_barrier
	ds_read_b128 v[140:143], v224
	ds_read_b128 v[156:159], v224 offset:1024
	ds_read_b128 v[160:163], v224 offset:2048
	ds_read_b128 v[164:167], v224 offset:3072
	ds_read_b128 v[168:171], v225
	ds_read_b128 v[172:175], v225 offset:1024
	ds_read_b128 v[176:179], v225 offset:2048
	ds_read_b128 v[180:183], v225 offset:3072
	s_add_i32 s83, 0, 0x1c000
	s_add_u32 s78, vcc_lo, 0x40000
	s_addc_u32 s79, vcc_hi, 0
	s_mov_b32 m0, s48
	v_lshl_add_u64 v[220:221], s[78:79], 0, v[130:131]
	ds_read_b128 v[184:187], v147 offset:32768
	ds_read_b128 v[188:191], v147 offset:33792
	ds_read_b128 v[192:195], v147 offset:34816
	ds_read_b128 v[196:199], v147 offset:35840
	ds_read_b128 v[200:203], v147 offset:36864
	ds_read_b128 v[204:207], v147 offset:37888
	ds_read_b128 v[208:211], v147 offset:38912
	ds_read_b128 v[212:215], v147 offset:39936
	global_load_lds_dwordx4 v[220:221], off
	s_mov_b32 m0, s49
	v_lshl_add_u64 v[220:221], s[78:79], 0, v[132:133]
	global_load_lds_dwordx4 v[220:221], off
	s_waitcnt vmcnt(8)
	s_waitcnt lgkmcnt(0)
	s_barrier
	s_setprio 1
	v_mfma_f32_16x16x32_bf16 v[126:129], v[140:143], v[184:187], v[126:129]
	v_mfma_f32_16x16x32_bf16 v[118:121], v[160:163], v[184:187], v[118:121]
	v_mfma_f32_16x16x32_bf16 v[110:113], v[140:143], v[192:195], v[110:113]
	v_mfma_f32_16x16x32_bf16 v[102:105], v[160:163], v[192:195], v[102:105]
	v_mfma_f32_16x16x32_bf16 v[94:97], v[140:143], v[200:203], v[94:97]
	v_mfma_f32_16x16x32_bf16 v[86:89], v[160:163], v[200:203], v[86:89]
	v_mfma_f32_16x16x32_bf16 v[78:81], v[140:143], v[208:211], v[78:81]
	v_mfma_f32_16x16x32_bf16 v[70:73], v[160:163], v[208:211], v[70:73]
	v_mfma_f32_16x16x32_bf16 v[126:129], v[156:159], v[188:191], v[126:129]
	v_mfma_f32_16x16x32_bf16 v[118:121], v[164:167], v[188:191], v[118:121]
	v_mfma_f32_16x16x32_bf16 v[110:113], v[156:159], v[196:199], v[110:113]
	v_mfma_f32_16x16x32_bf16 v[102:105], v[164:167], v[196:199], v[102:105]
	v_mfma_f32_16x16x32_bf16 v[94:97], v[156:159], v[204:207], v[94:97]
	v_mfma_f32_16x16x32_bf16 v[86:89], v[164:167], v[204:207], v[86:89]
	v_mfma_f32_16x16x32_bf16 v[78:81], v[156:159], v[212:215], v[78:81]
	v_mfma_f32_16x16x32_bf16 v[70:73], v[164:167], v[212:215], v[70:73]
	v_mfma_f32_16x16x32_bf16 v[122:125], v[168:171], v[184:187], v[122:125]
	v_mfma_f32_16x16x32_bf16 v[114:117], v[176:179], v[184:187], v[114:117]
	v_mfma_f32_16x16x32_bf16 v[106:109], v[168:171], v[192:195], v[106:109]
	v_mfma_f32_16x16x32_bf16 v[98:101], v[176:179], v[192:195], v[98:101]
	v_mfma_f32_16x16x32_bf16 v[90:93], v[168:171], v[200:203], v[90:93]
	v_mfma_f32_16x16x32_bf16 v[82:85], v[176:179], v[200:203], v[82:85]
	v_mfma_f32_16x16x32_bf16 v[74:77], v[168:171], v[208:211], v[74:77]
	v_mfma_f32_16x16x32_bf16 v[66:69], v[176:179], v[208:211], v[66:69]
	v_mfma_f32_16x16x32_bf16 v[122:125], v[172:175], v[188:191], v[122:125]
	v_mfma_f32_16x16x32_bf16 v[114:117], v[180:183], v[188:191], v[114:117]
	v_mfma_f32_16x16x32_bf16 v[106:109], v[172:175], v[196:199], v[106:109]
	v_mfma_f32_16x16x32_bf16 v[98:101], v[180:183], v[196:199], v[98:101]
	v_mfma_f32_16x16x32_bf16 v[90:93], v[172:175], v[204:207], v[90:93]
	v_mfma_f32_16x16x32_bf16 v[82:85], v[180:183], v[204:207], v[82:85]
	v_mfma_f32_16x16x32_bf16 v[74:77], v[172:175], v[212:215], v[74:77]
	v_mfma_f32_16x16x32_bf16 v[66:69], v[180:183], v[212:215], v[66:69]
	s_setprio 0
	s_barrier
	s_add_i32 s9, s45, 0x18000
	v_lshl_add_u64 v[148:149], v[148:149], 0, s[70:71]
	s_mov_b32 m0, s9
	ds_read_b128 v[184:187], v147 offset:49152
	ds_read_b128 v[188:191], v147 offset:50176
	ds_read_b128 v[192:195], v147 offset:51200
	ds_read_b128 v[196:199], v147 offset:52224
	ds_read_b128 v[200:203], v147 offset:53248
	ds_read_b128 v[204:207], v147 offset:54272
	ds_read_b128 v[208:211], v147 offset:55296
	ds_read_b128 v[212:215], v147 offset:56320
	global_load_lds_dwordx4 v[148:149], off
	s_add_i32 m0, s9, 0x2000
	s_add_u32 s38, s38, 0x40080
	v_lshl_add_u64 v[148:149], v[150:151], 0, s[70:71]
	s_addc_u32 s39, s39, 0
	s_add_i32 s9, s45, 0x1c000
	global_load_lds_dwordx4 v[148:149], off
	s_mov_b32 m0, s9
	v_lshl_add_u64 v[148:149], s[38:39], 0, v[0:1]
	global_load_lds_dwordx4 v[148:149], off
	s_add_i32 m0, s9, 0x2000
	v_lshl_add_u64 v[148:149], s[38:39], 0, v[134:135]
	global_load_lds_dwordx4 v[148:149], off
	s_mov_b32 m0, s50
	v_lshl_add_u64 v[148:149], v[216:217], 0, s[70:71]
	global_load_lds_dwordx4 v[148:149], off
	s_mov_b32 m0, s51
	v_lshl_add_u64 v[148:149], v[218:219], 0, s[70:71]
	global_load_lds_dwordx4 v[148:149], off
	s_add_i32 s75, s75, 2
	s_add_u32 s96, s96, 0x100
	s_addc_u32 s97, s97, 0
	s_add_u32 s53, s53, 0x100
	s_addc_u32 s61, s61, 0
	s_add_u32 s9, s96, 0xfffc0080
	s_addc_u32 s38, s97, -1
	s_cmp_eq_u32 s75, 12
	s_cselect_b32 vcc_hi, s25, s38
	s_cselect_b32 vcc_lo, s28, s9
	s_cselect_b32 s39, s23, s61
	s_cselect_b32 s38, s29, s53
	s_cmp_gt_u32 s75, 13
	s_waitcnt vmcnt(8)
	s_waitcnt lgkmcnt(0)
	s_barrier
	s_setprio 1
	v_mfma_f32_16x16x32_bf16 v[62:65], v[140:143], v[184:187], v[62:65]
	v_mfma_f32_16x16x32_bf16 v[54:57], v[160:163], v[184:187], v[54:57]
	v_mfma_f32_16x16x32_bf16 v[46:49], v[140:143], v[192:195], v[46:49]
	v_mfma_f32_16x16x32_bf16 v[38:41], v[160:163], v[192:195], v[38:41]
	v_mfma_f32_16x16x32_bf16 v[30:33], v[140:143], v[200:203], v[30:33]
	v_mfma_f32_16x16x32_bf16 v[22:25], v[160:163], v[200:203], v[22:25]
	v_mfma_f32_16x16x32_bf16 v[14:17], v[140:143], v[208:211], v[14:17]
	v_mfma_f32_16x16x32_bf16 v[6:9], v[160:163], v[208:211], v[6:9]
	v_mfma_f32_16x16x32_bf16 v[62:65], v[156:159], v[188:191], v[62:65]
	v_mfma_f32_16x16x32_bf16 v[54:57], v[164:167], v[188:191], v[54:57]
	v_mfma_f32_16x16x32_bf16 v[46:49], v[156:159], v[196:199], v[46:49]
	v_mfma_f32_16x16x32_bf16 v[38:41], v[164:167], v[196:199], v[38:41]
	v_mfma_f32_16x16x32_bf16 v[30:33], v[156:159], v[204:207], v[30:33]
	v_mfma_f32_16x16x32_bf16 v[22:25], v[164:167], v[204:207], v[22:25]
	v_mfma_f32_16x16x32_bf16 v[14:17], v[156:159], v[212:215], v[14:17]
	v_mfma_f32_16x16x32_bf16 v[6:9], v[164:167], v[212:215], v[6:9]
	v_mfma_f32_16x16x32_bf16 v[58:61], v[168:171], v[184:187], v[58:61]
	v_mfma_f32_16x16x32_bf16 v[50:53], v[176:179], v[184:187], v[50:53]
	v_mfma_f32_16x16x32_bf16 v[42:45], v[168:171], v[192:195], v[42:45]
	v_mfma_f32_16x16x32_bf16 v[34:37], v[176:179], v[192:195], v[34:37]
	v_mfma_f32_16x16x32_bf16 v[26:29], v[168:171], v[200:203], v[26:29]
	v_mfma_f32_16x16x32_bf16 v[18:21], v[176:179], v[200:203], v[18:21]
	v_mfma_f32_16x16x32_bf16 v[10:13], v[168:171], v[208:211], v[10:13]
	v_mfma_f32_16x16x32_bf16 v[2:5], v[176:179], v[208:211], v[2:5]
	v_mfma_f32_16x16x32_bf16 v[58:61], v[172:175], v[188:191], v[58:61]
	v_mfma_f32_16x16x32_bf16 v[50:53], v[180:183], v[188:191], v[50:53]
	v_mfma_f32_16x16x32_bf16 v[42:45], v[172:175], v[196:199], v[42:45]
	v_mfma_f32_16x16x32_bf16 v[34:37], v[180:183], v[196:199], v[34:37]
	v_mfma_f32_16x16x32_bf16 v[26:29], v[172:175], v[204:207], v[26:29]
	v_mfma_f32_16x16x32_bf16 v[18:21], v[180:183], v[204:207], v[18:21]
	v_mfma_f32_16x16x32_bf16 v[10:13], v[172:175], v[212:215], v[10:13]
	v_mfma_f32_16x16x32_bf16 v[2:5], v[180:183], v[212:215], v[2:5]
	s_setprio 0
	s_barrier
	s_cbranch_scc0 .LBB0_846
	s_and_b64 vcc, exec, s[14:15]
	s_cbranch_vccz .LBB0_849
	s_barrier
